# strategy 10 (f32 matrix cores for VALU f32 MAC): M1 GLA log-decay pre-activation (bias + 16x24 projection per token) via v_mfma_f32_32x32x2_f32 chains with permlane32_swap/bpermute operand arrangement
# speedup vs baseline: 1.0072x; 1.0072x over previous
; __device__ __forceinline__ float lo16(unsigned w) { return __uint_as_float(w << 16); }
; __device__ __forceinline__ float hi16(unsigned w) { return __uint_as_float(w & 0xffff0000u); }
; template <bool PHC>
; __device__ __forceinline__ void gla_pair(const KPD& kp, int l, int pair, unsigned char* lds, int tid, int lane, int wave, v4u& pz0, v4u& pz1, v4u& pw0, v4u& pw1, int next_pair) {
;     ...
;     { const v4u z0 = pz0, z1 = pz1;
;       z[0] = lo16(z0.x); z[1] = hi16(z0.x); z[2] = lo16(z0.y); z[3] = hi16(z0.y); z[4] = lo16(z0.z); z[5] = hi16(z0.z); z[6] = lo16(z0.w); z[7] = hi16(z0.w);
;       z[8] = lo16(z1.x); z[9] = hi16(z1.x); z[10] = lo16(z1.y); z[11] = hi16(z1.y); z[12] = lo16(z1.z); z[13] = hi16(z1.z); z[14] = lo16(z1.w); z[15] = hi16(z1.w); }
;     v4u qraw[3], kraw[3];
; #pragma unroll
;     for (int i = 0; i < 3; ++i) { qraw[i] = *((const v4u*)(prow + C_GQ + h * 48 + d0) + i); kraw[i] = *((const v4u*)(prow + C_GK + h * 48 + d0) + i); }
;     const int wvv[6] = {(int)pw0.x, (int)pw0.y, (int)pw0.z, (int)pw0.w, (int)pw1.x, (int)pw1.y};
;     const int bvv = (int)pw1.z;
;     float bc[24], tot[24];
; #pragma unroll
;     for (int c = 0; c < 24; ++c) {
;         float pre = __int_as_float(__builtin_amdgcn_readlane(bvv, c));
; #pragma unroll
;         for (int r = 0; r < 16; ++r) pre += z[r] * __int_as_float(__builtin_amdgcn_readlane(wvv[(24 * r + c) >> 6], (24 * r + c) & 63));
.LBB0_264:
	ds_read_b64 v[250:251], v204
	v_readfirstlane_b32 vcc_lo, v225
	s_lshl_b32 vcc_hi, s10, 2
	s_lshr_b32 vcc_lo, vcc_lo, 6
	s_and_b32 vcc_lo, vcc_lo, 3
	s_add_i32 vcc_lo, vcc_lo, vcc_hi
	s_mul_i32 vcc_lo, vcc_lo, 0x1800
	s_waitcnt lgkmcnt(0)
	v_readfirstlane_b32 s100, v250
	v_readfirstlane_b32 s101, v251
	v_mbcnt_lo_u32_b32 v250, -1, 0
	v_mbcnt_hi_u32_b32 v250, -1, v250
	s_add_u32 s100, s100, 0x3400000
	s_addc_u32 s101, s101, 0
	s_add_u32 s100, s100, vcc_lo
	s_addc_u32 s101, s101, 0
	v_lshlrev_b32_e32 v250, 2, v250
	v_add_u32_e32 v251, 0x1000, v250
	ds_read_b64 v[2:3], v204
	s_lshl_b32 s2, s12, 6
	s_and_b32 s46, s10, 3
	s_add_i32 s10, s11, s2
	v_add_u32_e32 v16, s10, v120
	s_waitcnt lgkmcnt(0)
	v_readfirstlane_b32 s3, v3
	v_readfirstlane_b32 s2, v2
	ds_read_b64 v[2:3], v204
	s_add_u32 s2, s2, 0x7800000
	s_addc_u32 s3, s3, 0
	v_mov_b64_e32 v[14:15], s[2:3]
	v_add_u32_e32 v6, s10, v37
	s_waitcnt lgkmcnt(0)
	v_readfirstlane_b32 s47, v3
	v_readfirstlane_b32 s48, v2
	ds_read_b64 v[2:3], v204
	v_add_u32_e32 v10, s10, v121
	v_mad_i64_i32 v[6:7], s[2:3], v6, s33, v[14:15]
	v_mad_i64_i32 v[10:11], s[2:3], v10, s33, v[14:15]
	s_waitcnt lgkmcnt(0)
	v_readfirstlane_b32 s50, v2
	v_add_u32_e32 v2, s10, v33
	v_readfirstlane_b32 s49, v3
	v_mad_i64_i32 v[2:3], s[2:3], v2, s33, v[14:15]
	v_mad_i64_i32 v[14:15], s[2:3], v16, s33, v[14:15]
	s_waitcnt vmcnt(0)
	v_mbcnt_lo_u32_b32 v211, -1, 0
	v_mbcnt_hi_u32_b32 v211, -1, v211
	v_lshrrev_b32_e32 v212, 5, v211
	v_and_b32_e32 v210, 31, v211
	v_mad_u32_u24 v210, v212, 24, v210
	v_add_u32_e32 v212, 0, v210
	v_and_b32_e32 v212, 63, v212
	v_lshlrev_b32_e32 v212, 2, v212
	ds_bpermute_b32 v197, v212, v26
	v_add_u32_e32 v212, 48, v210
	v_mov_b32_e32 v189, v212
	v_and_b32_e32 v212, 63, v212
	v_lshlrev_b32_e32 v212, 2, v212
	ds_bpermute_b32 v198, v212, v26
	ds_bpermute_b32 v177, v212, v27
	v_add_u32_e32 v212, 96, v210
	v_mov_b32_e32 v190, v212
	v_and_b32_e32 v212, 63, v212
	v_lshlrev_b32_e32 v212, 2, v212
	ds_bpermute_b32 v199, v212, v27
	ds_bpermute_b32 v178, v212, v28
	v_add_u32_e32 v212, 144, v210
	v_and_b32_e32 v212, 63, v212
	v_lshlrev_b32_e32 v212, 2, v212
	ds_bpermute_b32 v200, v212, v28
	v_add_u32_e32 v212, 192, v210
	v_and_b32_e32 v212, 63, v212
	v_lshlrev_b32_e32 v212, 2, v212
	ds_bpermute_b32 v201, v212, v29
	v_add_u32_e32 v212, 240, v210
	v_mov_b32_e32 v193, v212
	v_and_b32_e32 v212, 63, v212
	v_lshlrev_b32_e32 v212, 2, v212
	ds_bpermute_b32 v202, v212, v29
	ds_bpermute_b32 v181, v212, v30
	v_add_u32_e32 v212, 288, v210
	v_mov_b32_e32 v194, v212
	v_and_b32_e32 v212, 63, v212
	v_lshlrev_b32_e32 v212, 2, v212
	ds_bpermute_b32 v203, v212, v30
	ds_bpermute_b32 v186, v212, v31
	v_add_u32_e32 v212, 336, v210
	v_and_b32_e32 v212, 63, v212
	v_lshlrev_b32_e32 v212, 2, v212
	ds_bpermute_b32 v208, v212, v31
	s_waitcnt lgkmcnt(0)
	v_cmp_gt_u32_e32 vcc, 0x40, v189
	s_nop 1
	v_cndmask_b32_e32 v198, v177, v198, vcc
	v_cmp_gt_u32_e32 vcc, 0x80, v190
	s_nop 1
	v_cndmask_b32_e32 v199, v178, v199, vcc
	v_cmp_gt_u32_e32 vcc, 0x100, v193
	s_nop 1
	v_cndmask_b32_e32 v202, v181, v202, vcc
	v_cmp_gt_u32_e32 vcc, 0x140, v194
	s_nop 1
	v_cndmask_b32_e32 v203, v186, v203, vcc
	v_cmp_gt_u32_e32 vcc, 32, v211
	s_nop 1
	v_cndmask_b32_e32 v209, 0, v32, vcc
	v_mov_b32_e32 v196, 1.0
	v_lshlrev_b32_e32 v176, 16, v18
	v_and_b32_e32 v188, 0xffff0000, v18
	v_lshlrev_b32_e32 v177, 16, v19
	v_and_b32_e32 v189, 0xffff0000, v19
	v_lshlrev_b32_e32 v178, 16, v20
	v_and_b32_e32 v190, 0xffff0000, v20
	v_lshlrev_b32_e32 v179, 16, v21
	v_and_b32_e32 v191, 0xffff0000, v21
	v_lshlrev_b32_e32 v180, 16, v22
	v_and_b32_e32 v192, 0xffff0000, v22
	v_lshlrev_b32_e32 v181, 16, v23
	v_and_b32_e32 v193, 0xffff0000, v23
	v_lshlrev_b32_e32 v186, 16, v24
	v_and_b32_e32 v194, 0xffff0000, v24
	v_lshlrev_b32_e32 v187, 16, v25
	v_and_b32_e32 v195, 0xffff0000, v25
	v_permlane32_swap_b32_e32 v176, v188
	v_permlane32_swap_b32_e32 v177, v189
	v_permlane32_swap_b32_e32 v178, v190
	v_permlane32_swap_b32_e32 v179, v191
	v_permlane32_swap_b32_e32 v180, v192
	v_permlane32_swap_b32_e32 v181, v193
	v_permlane32_swap_b32_e32 v186, v194
	v_permlane32_swap_b32_e32 v187, v195
	v_mfma_f32_32x32x2_f32 v[160:175], v209, v196, 0
	v_mfma_f32_32x32x2_f32 v[226:241], v209, v196, 0
	v_mfma_f32_32x32x2_f32 v[160:175], v197, v176, v[160:175]
	v_mfma_f32_32x32x2_f32 v[226:241], v197, v188, v[226:241]
	v_mfma_f32_32x32x2_f32 v[160:175], v198, v177, v[160:175]
	v_mfma_f32_32x32x2_f32 v[226:241], v198, v189, v[226:241]
	v_mfma_f32_32x32x2_f32 v[160:175], v199, v178, v[160:175]
	v_mfma_f32_32x32x2_f32 v[226:241], v199, v190, v[226:241]
	v_mfma_f32_32x32x2_f32 v[160:175], v200, v179, v[160:175]
	v_mfma_f32_32x32x2_f32 v[226:241], v200, v191, v[226:241]
	v_mfma_f32_32x32x2_f32 v[160:175], v201, v180, v[160:175]
	v_mfma_f32_32x32x2_f32 v[226:241], v201, v192, v[226:241]
	v_mfma_f32_32x32x2_f32 v[160:175], v202, v181, v[160:175]
	v_mfma_f32_32x32x2_f32 v[226:241], v202, v193, v[226:241]
	v_mfma_f32_32x32x2_f32 v[160:175], v203, v186, v[160:175]
	v_mfma_f32_32x32x2_f32 v[226:241], v203, v194, v[226:241]
	v_mfma_f32_32x32x2_f32 v[160:175], v208, v187, v[160:175]
	v_mfma_f32_32x32x2_f32 v[226:241], v208, v195, v[226:241]
	s_nop 15
	s_nop 1
	v_permlane32_swap_b32_e32 v160, v226
	v_permlane32_swap_b32_e32 v161, v227
	v_permlane32_swap_b32_e32 v162, v228
	v_permlane32_swap_b32_e32 v163, v229
	v_permlane32_swap_b32_e32 v164, v230
	v_permlane32_swap_b32_e32 v165, v231
	v_permlane32_swap_b32_e32 v166, v232
	v_permlane32_swap_b32_e32 v167, v233
	v_permlane32_swap_b32_e32 v168, v234
	v_permlane32_swap_b32_e32 v169, v235
	v_permlane32_swap_b32_e32 v170, v236
	v_permlane32_swap_b32_e32 v171, v237
;     __device__ __forceinline__ unsigned char* ws() const { return (unsigned char*)(__attribute__((address_space(1))) unsigned char*)ld(23); }
; __device__ __forceinline__ float lo16(unsigned w) { return __uint_as_float(w << 16); }
; __device__ __forceinline__ float hi16(unsigned w) { return __uint_as_float(w & 0xffff0000u); }
; template <bool PHC>
; __device__ __forceinline__ void gla_pair(const KPD& kp, int l, int pair, unsigned char* lds, int tid, int lane, int wave, v4u& pz0, v4u& pz1, v4u& pw0, v4u& pw1, int next_pair) {
;     ...
;     for (int i = 0; i < 3; ++i) { const int idx = t4 + 256 * i; vpre[i] = *(const v4u*)(P + (size_t)(rowbase + idx / 12) * INP + C_GV + h * 96 + 8 * (idx % 12)); }
;     v2u spre[9];
;     if constexpr (PHC) { const bf16* SI = (const bf16*)(kp.ws() + WS_SI);
; #pragma unroll
;         for (int i = 0; i < 9; ++i) { const int idx = t4 + 256 * i; const int dd = idx / 1152, e = (idx % 1152) * 4;
;             spre[i] = *(const v2u*)(SI + ((size_t)((dd * 4 + b) * NCH + n) * 4 + h) * 4608 + e); }
;     }
;     float z[16];
;     { const v4u z0 = pz0, z1 = pz1;
;       z[0] = lo16(z0.x); z[1] = hi16(z0.x); z[2] = lo16(z0.y); z[3] = hi16(z0.y); z[4] = lo16(z0.z); z[5] = hi16(z0.z); z[6] = lo16(z0.w); z[7] = hi16(z0.w);
;       z[8] = lo16(z1.x); z[9] = hi16(z1.x); z[10] = lo16(z1.y); z[11] = hi16(z1.y); z[12] = lo16(z1.z); z[13] = hi16(z1.z); z[14] = lo16(z1.w); z[15] = hi16(z1.w); }
;     v4u qraw[3], kraw[3];
; #pragma unroll
;     for (int i = 0; i < 3; ++i) { qraw[i] = *((const v4u*)(prow + C_GQ + h * 48 + d0) + i); kraw[i] = *((const v4u*)(prow + C_GK + h * 48 + d0) + i); }
;     const int wvv[6] = {(int)pw0.x, (int)pw0.y, (int)pw0.z, (int)pw0.w, (int)pw1.x, (int)pw1.y};
;     const int bvv = (int)pw1.z;
;     float bc[24], tot[24];
; #pragma unroll
;     for (int c = 0; c < 24; ++c) {
;         float pre = __int_as_float(__builtin_amdgcn_readlane(bvv, c));
; #pragma unroll
;         for (int r = 0; r < 16; ++r) pre += z[r] * __int_as_float(__builtin_amdgcn_readlane(wvv[(24 * r + c) >> 6], (24 * r + c) & 63));
;         const float la = (fminf(pre, 0.f) - __logf(1.f + __expf(-fabsf(pre)))) * (1.f / 16.f);
;         const float inc = wave_incl_scan(la);
;         const float total = __int_as_float(__builtin_amdgcn_readlane(__float_as_int(inc), 63));
;         bc[c] = dir ? (total - inc + la) : inc; tot[c] = total;
	v_lshlrev_b32_e32 v64, 16, v18
	v_and_b32_e32 v63, 0xffff0000, v18
	v_lshlrev_b32_e32 v50, 16, v25
	v_and_b32_e32 v51, 0xffff0000, v25
	s_mov_b32 s72, 0xbfb8aa3b
	s_mul_i32 s78, s46, 0xc0
	s_mul_i32 s51, s46, 48
	v_lshl_add_u64 v[2:3], v[2:3], 0, s[78:79]
	v_lshl_add_u64 v[6:7], v[6:7], 0, s[78:79]
	v_lshl_add_u64 v[10:11], v[10:11], 0, s[78:79]
	s_lshl_b32 s78, s51, 1
	v_lshl_add_u64 v[14:15], v[14:15], 0, s[78:79]
	s_lshl_b32 s78, s40, 1
	v_mov_b32_e32 v38, v160
	v_min_f32_e32 v65, 0, v38
	v_mul_f32_e64 v38, |v38|, s72
	v_exp_f32_e32 v38, v38
	v_lshl_add_u64 v[46:47], v[14:15], 0, s[78:79]
	s_mov_b32 s78, 0x800000
	s_mov_b32 s87, 0x3f317217
	v_add_f32_e32 v38, 1.0, v38
	v_cmp_gt_f32_e32 vcc, s78, v38
	s_mov_b32 s97, 0x7f800000
	s_nop 0
	v_cndmask_b32_e64 v66, 0, 32, vcc
	v_ldexp_f32 v38, v38, v66
	v_log_f32_e32 v38, v38
	s_nop 0
	v_mul_f32_e32 v66, 0x3f317217, v38
	v_fma_f32 v66, v38, s87, -v66
	v_fmac_f32_e32 v66, 0x3377d1cf, v38
	v_fmac_f32_e32 v66, 0x3f317217, v38
	v_cmp_lt_f32_e64 s[10:11], |v38|, s97
	s_nop 1
	v_cndmask_b32_e64 v38, v38, v66, s[10:11]
	v_cndmask_b32_e32 v66, 0, v222, vcc
	v_sub_f32_e32 v38, v38, v66
	v_sub_f32_e32 v38, v65, v38
	v_mul_f32_e32 v65, 0x3d800000, v38
	v_mov_b32_e32 v66, v35
	s_nop 0
	v_mov_b32_dpp v65, v65 row_shr:1 row_mask:0xf bank_mask:0xf bound_ctrl:1
	v_fmac_f32_e32 v65, 0x3d800000, v38
	s_nop 1
	v_add_f32_dpp v65, v65, v65 row_shr:2 row_mask:0xf bank_mask:0xf bound_ctrl:1
	s_nop 1
	v_add_f32_dpp v65, v65, v65 row_shr:4 row_mask:0xf bank_mask:0xf bound_ctrl:1
	s_nop 1
	v_add_f32_dpp v65, v65, v65 row_shr:8 row_mask:0xf bank_mask:0xf bound_ctrl:1
	s_nop 1
	v_mov_b32_dpp v66, v65 row_bcast:15 row_mask:0xa bank_mask:0xf
	v_add_f32_e32 v65, v65, v66
	v_mov_b32_e32 v66, v35
	s_nop 0
	v_mov_b32_dpp v66, v65 row_bcast:31 row_mask:0xc bank_mask:0xf
	v_add_f32_e32 v65, v65, v66
	s_nop 0
	v_readlane_b32 s54, v65, 63
	s_nop 1
	v_sub_f32_e32 v66, s54, v65
	v_fmac_f32_e32 v66, 0x3d800000, v38
	v_cndmask_b32_e64 v65, v66, v65, s[0:1]
	global_store_dword v250, v65, s[100:101]
	v_mov_b32_e32 v38, v161
	v_min_f32_e32 v39, 0, v38
	v_mul_f32_e64 v38, |v38|, s72
	v_exp_f32_e32 v38, v38
	s_nop 0
	v_add_f32_e32 v38, 1.0, v38
	v_cmp_gt_f32_e32 vcc, s78, v38
	s_nop 1
	v_cndmask_b32_e64 v66, 0, 32, vcc
	v_ldexp_f32 v38, v38, v66
	v_log_f32_e32 v38, v38
	v_mov_b32_e32 v79, v35
	v_mul_f32_e32 v66, 0x3f317217, v38
	v_fma_f32 v66, v38, s87, -v66
	v_fmac_f32_e32 v66, 0x3377d1cf, v38
	v_fmac_f32_e32 v66, 0x3f317217, v38
	v_cmp_lt_f32_e64 s[10:11], |v38|, s97
	s_nop 1
	v_cndmask_b32_e64 v38, v38, v66, s[10:11]
	v_cndmask_b32_e32 v66, 0, v222, vcc
	v_sub_f32_e32 v38, v38, v66
	v_sub_f32_e32 v38, v39, v38
	v_mul_f32_e32 v39, 0x3d800000, v38
	v_mov_b32_e32 v66, v35
	s_nop 0
	v_mov_b32_dpp v39, v39 row_shr:1 row_mask:0xf bank_mask:0xf bound_ctrl:1
	v_fmac_f32_e32 v39, 0x3d800000, v38
	s_nop 1
	v_add_f32_dpp v39, v39, v39 row_shr:2 row_mask:0xf bank_mask:0xf bound_ctrl:1
	v_lshl_add_u64 v[2:3], v[2:3], 0, v[78:79]
	s_nop 0
	v_add_f32_dpp v39, v39, v39 row_shr:4 row_mask:0xf bank_mask:0xf bound_ctrl:1
	v_readlane_b32 s12, v31, 21
	s_nop 0
	v_add_f32_dpp v39, v39, v39 row_shr:8 row_mask:0xf bank_mask:0xf bound_ctrl:1
	v_readlane_b32 s13, v31, 45
	s_nop 0
	v_mov_b32_dpp v66, v39 row_bcast:15 row_mask:0xa bank_mask:0xf
	v_add_f32_e32 v39, v39, v66
	v_mov_b32_e32 v66, v35
	v_mov_b32_e32 v81, v35
	v_mov_b32_dpp v66, v39 row_bcast:31 row_mask:0xc bank_mask:0xf
	v_add_f32_e32 v39, v39, v66
	s_nop 0
	v_readlane_b32 s36, v39, 63
	v_lshl_add_u64 v[6:7], v[6:7], 0, v[80:81]
	s_nop 0
	v_sub_f32_e32 v66, s36, v39
	v_fmac_f32_e32 v66, 0x3d800000, v38
	v_cndmask_b32_e64 v66, v66, v39, s[0:1]
	global_store_dword v250, v66, s[100:101] offset:256
	v_mov_b32_e32 v83, v35
	v_mov_b32_e32 v38, v162
	v_min_f32_e32 v39, 0, v38
	v_mul_f32_e64 v38, |v38|, s72
	v_exp_f32_e32 v38, v38
	v_lshl_add_u64 v[10:11], v[10:11], 0, v[82:83]
	v_add_f32_e32 v38, 1.0, v38
	v_cmp_gt_f32_e32 vcc, s78, v38
	s_nop 1
	v_cndmask_b32_e64 v40, 0, 32, vcc
	v_ldexp_f32 v38, v38, v40
	v_log_f32_e32 v38, v38
	global_load_dwordx4 v[2:5], v[2:3], off offset:768
	v_mul_f32_e32 v40, 0x3f317217, v38
	v_fma_f32 v40, v38, s87, -v40
	v_fmac_f32_e32 v40, 0x3377d1cf, v38
	v_fmac_f32_e32 v40, 0x3f317217, v38
	v_cmp_lt_f32_e64 s[10:11], |v38|, s97
	s_nop 1
	v_cndmask_b32_e64 v38, v38, v40, s[10:11]
	v_cndmask_b32_e32 v40, 0, v222, vcc
	v_sub_f32_e32 v38, v38, v40
	v_sub_f32_e32 v38, v39, v38
	v_mul_f32_e32 v39, 0x3d800000, v38
	v_mov_b32_e32 v40, v35
	s_nop 0
	v_mov_b32_dpp v39, v39 row_shr:1 row_mask:0xf bank_mask:0xf bound_ctrl:1
	v_fmac_f32_e32 v39, 0x3d800000, v38
	s_nop 1
	v_add_f32_dpp v39, v39, v39 row_shr:2 row_mask:0xf bank_mask:0xf bound_ctrl:1
	global_load_dwordx4 v[6:9], v[6:7], off offset:768
	s_nop 0
	v_add_f32_dpp v39, v39, v39 row_shr:4 row_mask:0xf bank_mask:0xf bound_ctrl:1
	global_load_dwordx4 v[10:13], v[10:11], off offset:768
	s_nop 0
	v_add_f32_dpp v39, v39, v39 row_shr:8 row_mask:0xf bank_mask:0xf bound_ctrl:1
	global_load_dwordx4 v[14:17], v[46:47], off offset:416
	global_load_dwordx4 v[42:45], v[46:47], off offset:400
	global_load_dwordx4 v[46:49], v[46:47], off offset:384
	v_mov_b32_dpp v40, v39 row_bcast:15 row_mask:0xa bank_mask:0xf
	v_add_f32_e32 v39, v39, v40
	v_mov_b32_e32 v40, v35
	s_nop 0
	v_mov_b32_dpp v40, v39 row_bcast:31 row_mask:0xc bank_mask:0xf
	v_add_f32_e32 v39, v39, v40
	s_nop 0
	v_readlane_b32 s34, v39, 63
	s_nop 1
	v_sub_f32_e32 v40, s34, v39
	v_fmac_f32_e32 v40, 0x3d800000, v38
	v_cndmask_b32_e64 v67, v40, v39, s[0:1]
	global_store_dword v250, v67, s[100:101] offset:512
	v_mov_b32_e32 v38, v163
	v_min_f32_e32 v39, 0, v38
	v_mul_f32_e64 v38, |v38|, s72
	v_exp_f32_e32 v38, v38
	s_nop 0
	v_add_f32_e32 v38, 1.0, v38
	v_cmp_gt_f32_e32 vcc, s78, v38
	s_nop 1
	v_cndmask_b32_e64 v40, 0, 32, vcc
	v_ldexp_f32 v38, v38, v40
	v_log_f32_e32 v38, v38
	s_nop 0
	v_mul_f32_e32 v40, 0x3f317217, v38
	v_fma_f32 v40, v38, s87, -v40
	v_fmac_f32_e32 v40, 0x3377d1cf, v38
	v_fmac_f32_e32 v40, 0x3f317217, v38
	v_cmp_lt_f32_e64 s[10:11], |v38|, s97
	s_nop 1
	v_cndmask_b32_e64 v38, v38, v40, s[10:11]
	v_cndmask_b32_e32 v40, 0, v222, vcc
	v_sub_f32_e32 v38, v38, v40
	v_sub_f32_e32 v38, v39, v38
	v_mul_f32_e32 v39, 0x3d800000, v38
	v_mov_b32_e32 v40, v35
	s_nop 0
	v_mov_b32_dpp v39, v39 row_shr:1 row_mask:0xf bank_mask:0xf bound_ctrl:1
	v_fmac_f32_e32 v39, 0x3d800000, v38
	s_nop 1
	v_add_f32_dpp v39, v39, v39 row_shr:2 row_mask:0xf bank_mask:0xf bound_ctrl:1
	s_waitcnt vmcnt(0)
; template <bool PHC>
; __device__ __forceinline__ void gla_pair(const KPD& kp, int l, int pair, unsigned char* lds, int tid, int lane, int wave, v4u& pz0, v4u& pz1, v4u& pw0, v4u& pw1, int next_pair) {
;     ...
;     for (int c = 0; c < 24; ++c) {
;         float pre = __int_as_float(__builtin_amdgcn_readlane(bvv, c));
; #pragma unroll
;         for (int r = 0; r < 16; ++r) pre += z[r] * __int_as_float(__builtin_amdgcn_readlane(wvv[(24 * r + c) >> 6], (24 * r + c) & 63));
;         const float la = (fminf(pre, 0.f) - __logf(1.f + __expf(-fabsf(pre)))) * (1.f / 16.f);
;         const float inc = wave_incl_scan(la);
;         const float total = __int_as_float(__builtin_amdgcn_readlane(__float_as_int(inc), 63));
;         bc[c] = dir ? (total - inc + la) : inc; tot[c] = total;
	v_lshlrev_b32_e32 v41, 16, v47
	v_add_f32_dpp v39, v39, v39 row_shr:4 row_mask:0xf bank_mask:0xf bound_ctrl:1
	s_nop 1
	v_add_f32_dpp v39, v39, v39 row_shr:8 row_mask:0xf bank_mask:0xf bound_ctrl:1
	s_nop 1
	v_mov_b32_dpp v40, v39 row_bcast:15 row_mask:0xa bank_mask:0xf
	v_add_f32_e32 v39, v39, v40
	v_mov_b32_e32 v40, v35
	s_nop 0
	v_mov_b32_dpp v40, v39 row_bcast:31 row_mask:0xc bank_mask:0xf
	v_add_f32_e32 v39, v39, v40
	s_nop 0
	v_readlane_b32 s30, v39, 63
	s_nop 1
	v_sub_f32_e32 v40, s30, v39
	v_fmac_f32_e32 v40, 0x3d800000, v38
	v_cndmask_b32_e64 v68, v40, v39, s[0:1]
	global_store_dword v250, v68, s[100:101] offset:768
	v_mov_b32_e32 v38, v226
	v_min_f32_e32 v39, 0, v38
	v_mul_f32_e64 v38, |v38|, s72
	v_exp_f32_e32 v38, v38
	s_nop 0
	v_add_f32_e32 v38, 1.0, v38
	v_cmp_gt_f32_e32 vcc, s78, v38
	s_nop 1
	v_cndmask_b32_e64 v40, 0, 32, vcc
	v_ldexp_f32 v38, v38, v40
	v_log_f32_e32 v38, v38
	s_nop 0
	v_mul_f32_e32 v40, 0x3f317217, v38
	v_fma_f32 v40, v38, s87, -v40
	v_fmac_f32_e32 v40, 0x3377d1cf, v38
	v_fmac_f32_e32 v40, 0x3f317217, v38
	v_cmp_lt_f32_e64 s[10:11], |v38|, s97
	s_nop 1
	v_cndmask_b32_e64 v38, v38, v40, s[10:11]
	v_cndmask_b32_e32 v40, 0, v222, vcc
	v_sub_f32_e32 v38, v38, v40
	v_sub_f32_e32 v38, v39, v38
	v_mul_f32_e32 v39, 0x3d800000, v38
	v_mov_b32_e32 v40, v35
	s_nop 0
	v_mov_b32_dpp v39, v39 row_shr:1 row_mask:0xf bank_mask:0xf bound_ctrl:1
	v_fmac_f32_e32 v39, 0x3d800000, v38
	s_nop 1
	v_add_f32_dpp v39, v39, v39 row_shr:2 row_mask:0xf bank_mask:0xf bound_ctrl:1
	s_nop 1
	v_add_f32_dpp v39, v39, v39 row_shr:4 row_mask:0xf bank_mask:0xf bound_ctrl:1
	s_nop 1
	v_add_f32_dpp v39, v39, v39 row_shr:8 row_mask:0xf bank_mask:0xf bound_ctrl:1
	s_nop 1
	v_mov_b32_dpp v40, v39 row_bcast:15 row_mask:0xa bank_mask:0xf
	v_add_f32_e32 v39, v39, v40
	v_mov_b32_e32 v40, v35
	s_nop 0
	v_mov_b32_dpp v40, v39 row_bcast:31 row_mask:0xc bank_mask:0xf
	v_add_f32_e32 v39, v39, v40
	s_nop 0
	v_readlane_b32 s28, v39, 63
	s_nop 1
	v_sub_f32_e32 v40, s28, v39
	v_fmac_f32_e32 v40, 0x3d800000, v38
	v_cndmask_b32_e64 v69, v40, v39, s[0:1]
	global_store_dword v250, v69, s[100:101] offset:1024
	v_mov_b32_e32 v38, v227
	v_min_f32_e32 v39, 0, v38
	v_mul_f32_e64 v38, |v38|, s72
	v_exp_f32_e32 v38, v38
	s_nop 0
	v_add_f32_e32 v38, 1.0, v38
	v_cmp_gt_f32_e32 vcc, s78, v38
	s_nop 1
	v_cndmask_b32_e64 v40, 0, 32, vcc
	v_ldexp_f32 v38, v38, v40
	v_log_f32_e32 v38, v38
	s_nop 0
	v_mul_f32_e32 v40, 0x3f317217, v38
	v_fma_f32 v40, v38, s87, -v40
	v_fmac_f32_e32 v40, 0x3377d1cf, v38
	v_fmac_f32_e32 v40, 0x3f317217, v38
	v_cmp_lt_f32_e64 s[10:11], |v38|, s97
	s_nop 1
	v_cndmask_b32_e64 v38, v38, v40, s[10:11]
	v_cndmask_b32_e32 v40, 0, v222, vcc
	v_sub_f32_e32 v38, v38, v40
	v_sub_f32_e32 v38, v39, v38
	v_mul_f32_e32 v39, 0x3d800000, v38
	s_nop 1
	v_mov_b32_dpp v39, v39 row_shr:1 row_mask:0xf bank_mask:0xf bound_ctrl:1
	v_fmac_f32_e32 v39, 0x3d800000, v38
	s_nop 1
	v_add_f32_dpp v39, v39, v39 row_shr:2 row_mask:0xf bank_mask:0xf bound_ctrl:1
	v_mov_b32_e32 v40, v35
	s_nop 0
	v_add_f32_dpp v39, v39, v39 row_shr:4 row_mask:0xf bank_mask:0xf bound_ctrl:1
	s_nop 1
	v_add_f32_dpp v39, v39, v39 row_shr:8 row_mask:0xf bank_mask:0xf bound_ctrl:1
	s_nop 1
	v_mov_b32_dpp v40, v39 row_bcast:15 row_mask:0xa bank_mask:0xf
	v_add_f32_e32 v39, v39, v40
	v_mov_b32_e32 v40, v35
	s_nop 0
	v_mov_b32_dpp v40, v39 row_bcast:31 row_mask:0xc bank_mask:0xf
	v_add_f32_e32 v39, v39, v40
	s_nop 0
	v_readlane_b32 s29, v39, 63
	s_nop 1
	v_sub_f32_e32 v40, s29, v39
	v_fmac_f32_e32 v40, 0x3d800000, v38
	v_cndmask_b32_e64 v79, v40, v39, s[0:1]
	global_store_dword v250, v79, s[100:101] offset:1280
	v_mov_b32_e32 v38, v228
	v_min_f32_e32 v39, 0, v38
	v_mul_f32_e64 v38, |v38|, s72
	v_exp_f32_e32 v38, v38
	s_nop 0
	v_add_f32_e32 v38, 1.0, v38
	v_cmp_gt_f32_e32 vcc, s78, v38
	s_nop 1
	v_cndmask_b32_e64 v40, 0, 32, vcc
	v_ldexp_f32 v38, v38, v40
	v_log_f32_e32 v38, v38
	s_nop 0
	v_mul_f32_e32 v40, 0x3f317217, v38
	v_fma_f32 v40, v38, s87, -v40
	v_fmac_f32_e32 v40, 0x3377d1cf, v38
	v_fmac_f32_e32 v40, 0x3f317217, v38
	v_cmp_lt_f32_e64 s[10:11], |v38|, s97
	s_nop 1
	v_cndmask_b32_e64 v38, v38, v40, s[10:11]
	v_cndmask_b32_e32 v40, 0, v222, vcc
	v_sub_f32_e32 v38, v38, v40
	v_sub_f32_e32 v38, v39, v38
	v_mul_f32_e32 v39, 0x3d800000, v38
	v_mov_b32_e32 v40, v35
	s_nop 0
	v_mov_b32_dpp v39, v39 row_shr:1 row_mask:0xf bank_mask:0xf bound_ctrl:1
	v_fmac_f32_e32 v39, 0x3d800000, v38
	s_nop 1
	v_add_f32_dpp v39, v39, v39 row_shr:2 row_mask:0xf bank_mask:0xf bound_ctrl:1
	s_nop 1
	v_add_f32_dpp v39, v39, v39 row_shr:4 row_mask:0xf bank_mask:0xf bound_ctrl:1
	s_nop 1
	v_add_f32_dpp v39, v39, v39 row_shr:8 row_mask:0xf bank_mask:0xf bound_ctrl:1
	s_nop 1
	v_mov_b32_dpp v40, v39 row_bcast:15 row_mask:0xa bank_mask:0xf
	v_add_f32_e32 v39, v39, v40
	v_mov_b32_e32 v40, v35
	s_nop 0
	v_mov_b32_dpp v40, v39 row_bcast:31 row_mask:0xc bank_mask:0xf
	v_add_f32_e32 v39, v39, v40
	s_nop 0
	v_readlane_b32 s31, v39, 63
	s_nop 1
	v_sub_f32_e32 v40, s31, v39
	v_fmac_f32_e32 v40, 0x3d800000, v38
	v_cndmask_b32_e64 v81, v40, v39, s[0:1]
	global_store_dword v250, v81, s[100:101] offset:1536
	v_mov_b32_e32 v38, v229
	v_min_f32_e32 v39, 0, v38
	v_mul_f32_e64 v38, |v38|, s72
	v_exp_f32_e32 v38, v38
	s_nop 0
	v_add_f32_e32 v38, 1.0, v38
	v_cmp_gt_f32_e32 vcc, s78, v38
	s_nop 1
	v_cndmask_b32_e64 v40, 0, 32, vcc
	v_ldexp_f32 v38, v38, v40
	v_log_f32_e32 v38, v38
	s_nop 0
	v_mul_f32_e32 v40, 0x3f317217, v38
	v_fma_f32 v40, v38, s87, -v40
	v_fmac_f32_e32 v40, 0x3377d1cf, v38
	v_fmac_f32_e32 v40, 0x3f317217, v38
	v_cmp_lt_f32_e64 s[10:11], |v38|, s97
	s_nop 1
	v_cndmask_b32_e64 v38, v38, v40, s[10:11]
	v_cndmask_b32_e32 v40, 0, v222, vcc
; template <bool PHC>
; __device__ __forceinline__ void gla_pair(const KPD& kp, int l, int pair, unsigned char* lds, int tid, int lane, int wave, v4u& pz0, v4u& pz1, v4u& pw0, v4u& pw1, int next_pair) {
;     ...
;     for (int c = 0; c < 24; ++c) {
;         float pre = __int_as_float(__builtin_amdgcn_readlane(bvv, c));
; #pragma unroll
;         for (int r = 0; r < 16; ++r) pre += z[r] * __int_as_float(__builtin_amdgcn_readlane(wvv[(24 * r + c) >> 6], (24 * r + c) & 63));
;         const float la = (fminf(pre, 0.f) - __logf(1.f + __expf(-fabsf(pre)))) * (1.f / 16.f);
;         const float inc = wave_incl_scan(la);
;         const float total = __int_as_float(__builtin_amdgcn_readlane(__float_as_int(inc), 63));
;         bc[c] = dir ? (total - inc + la) : inc; tot[c] = total;
	v_sub_f32_e32 v38, v38, v40
	v_sub_f32_e32 v38, v39, v38
	v_mul_f32_e32 v39, 0x3d800000, v38
	v_mov_b32_e32 v40, v35
	s_nop 0
	v_mov_b32_dpp v39, v39 row_shr:1 row_mask:0xf bank_mask:0xf bound_ctrl:1
	v_fmac_f32_e32 v39, 0x3d800000, v38
	s_nop 1
	v_add_f32_dpp v39, v39, v39 row_shr:2 row_mask:0xf bank_mask:0xf bound_ctrl:1
	s_nop 1
	v_add_f32_dpp v39, v39, v39 row_shr:4 row_mask:0xf bank_mask:0xf bound_ctrl:1
	s_nop 1
	v_add_f32_dpp v39, v39, v39 row_shr:8 row_mask:0xf bank_mask:0xf bound_ctrl:1
	s_nop 1
	v_mov_b32_dpp v40, v39 row_bcast:15 row_mask:0xa bank_mask:0xf
	v_add_f32_e32 v39, v39, v40
	v_mov_b32_e32 v40, v35
	s_nop 0
	v_mov_b32_dpp v40, v39 row_bcast:31 row_mask:0xc bank_mask:0xf
	v_add_f32_e32 v39, v39, v40
	s_nop 0
	v_readlane_b32 s35, v39, 63
	s_nop 1
	v_sub_f32_e32 v40, s35, v39
	v_fmac_f32_e32 v40, 0x3d800000, v38
	v_cndmask_b32_e64 v83, v40, v39, s[0:1]
	global_store_dword v250, v83, s[100:101] offset:1792
	v_mov_b32_e32 v38, v164
	v_min_f32_e32 v39, 0, v38
	v_mul_f32_e64 v38, |v38|, s72
	v_exp_f32_e32 v38, v38
	s_nop 0
	v_add_f32_e32 v38, 1.0, v38
	v_cmp_gt_f32_e32 vcc, s78, v38
	s_nop 1
	v_cndmask_b32_e64 v40, 0, 32, vcc
	v_ldexp_f32 v38, v38, v40
	v_log_f32_e32 v38, v38
	s_nop 0
	v_mul_f32_e32 v40, 0x3f317217, v38
	v_fma_f32 v40, v38, s87, -v40
	v_fmac_f32_e32 v40, 0x3377d1cf, v38
	v_fmac_f32_e32 v40, 0x3f317217, v38
	v_cmp_lt_f32_e64 s[10:11], |v38|, s97
	s_nop 1
	v_cndmask_b32_e64 v38, v38, v40, s[10:11]
	v_cndmask_b32_e32 v40, 0, v222, vcc
	v_sub_f32_e32 v38, v38, v40
	v_sub_f32_e32 v38, v39, v38
	v_mul_f32_e32 v39, 0x3d800000, v38
	v_mov_b32_e32 v40, v35
	s_nop 0
	v_mov_b32_dpp v39, v39 row_shr:1 row_mask:0xf bank_mask:0xf bound_ctrl:1
	v_fmac_f32_e32 v39, 0x3d800000, v38
	s_nop 1
	v_add_f32_dpp v39, v39, v39 row_shr:2 row_mask:0xf bank_mask:0xf bound_ctrl:1
	s_nop 1
	v_add_f32_dpp v39, v39, v39 row_shr:4 row_mask:0xf bank_mask:0xf bound_ctrl:1
	s_nop 1
	v_add_f32_dpp v39, v39, v39 row_shr:8 row_mask:0xf bank_mask:0xf bound_ctrl:1
	s_nop 1
	v_mov_b32_dpp v40, v39 row_bcast:15 row_mask:0xa bank_mask:0xf
	v_add_f32_e32 v39, v39, v40
	v_mov_b32_e32 v40, v35
	s_nop 0
	v_mov_b32_dpp v40, v39 row_bcast:31 row_mask:0xc bank_mask:0xf
	v_add_f32_e32 v39, v39, v40
	s_nop 0
	v_readlane_b32 s37, v39, 63
	s_nop 1
	v_sub_f32_e32 v40, s37, v39
	v_fmac_f32_e32 v40, 0x3d800000, v38
	v_cndmask_b32_e64 v85, v40, v39, s[0:1]
	global_store_dword v250, v85, s[100:101] offset:2048
	v_mov_b32_e32 v38, v165
	v_min_f32_e32 v39, 0, v38
	v_mul_f32_e64 v38, |v38|, s72
	v_exp_f32_e32 v38, v38
	s_nop 0
	v_add_f32_e32 v38, 1.0, v38
	v_cmp_gt_f32_e32 vcc, s78, v38
	s_nop 1
	v_cndmask_b32_e64 v40, 0, 32, vcc
	v_ldexp_f32 v38, v38, v40
	v_log_f32_e32 v38, v38
	s_nop 0
	v_mul_f32_e32 v40, 0x3f317217, v38
	v_fma_f32 v40, v38, s87, -v40
	v_fmac_f32_e32 v40, 0x3377d1cf, v38
	v_fmac_f32_e32 v40, 0x3f317217, v38
	v_cmp_lt_f32_e64 s[10:11], |v38|, s97
	s_nop 1
	v_cndmask_b32_e64 v38, v38, v40, s[10:11]
	v_cndmask_b32_e32 v40, 0, v222, vcc
	v_sub_f32_e32 v38, v38, v40
	v_sub_f32_e32 v38, v39, v38
	v_mul_f32_e32 v39, 0x3d800000, v38
	v_mov_b32_e32 v40, v35
	s_nop 0
	v_mov_b32_dpp v39, v39 row_shr:1 row_mask:0xf bank_mask:0xf bound_ctrl:1
	v_fmac_f32_e32 v39, 0x3d800000, v38
	s_nop 1
	v_add_f32_dpp v39, v39, v39 row_shr:2 row_mask:0xf bank_mask:0xf bound_ctrl:1
	s_nop 1
	v_add_f32_dpp v39, v39, v39 row_shr:4 row_mask:0xf bank_mask:0xf bound_ctrl:1
	s_nop 1
	v_add_f32_dpp v39, v39, v39 row_shr:8 row_mask:0xf bank_mask:0xf bound_ctrl:1
	s_nop 1
	v_mov_b32_dpp v40, v39 row_bcast:15 row_mask:0xa bank_mask:0xf
	v_add_f32_e32 v39, v39, v40
	v_mov_b32_e32 v40, v35
	s_nop 0
	v_mov_b32_dpp v40, v39 row_bcast:31 row_mask:0xc bank_mask:0xf
	v_add_f32_e32 v39, v39, v40
	s_nop 0
	v_readlane_b32 s55, v39, 63
	s_nop 1
	v_sub_f32_e32 v40, s55, v39
	v_fmac_f32_e32 v40, 0x3d800000, v38
	v_cndmask_b32_e64 v87, v40, v39, s[0:1]
	global_store_dword v250, v87, s[100:101] offset:2304
	v_mov_b32_e32 v38, v166
	v_min_f32_e32 v39, 0, v38
	v_mul_f32_e64 v38, |v38|, s72
	v_exp_f32_e32 v38, v38
	s_nop 0
	v_add_f32_e32 v38, 1.0, v38
	v_cmp_gt_f32_e32 vcc, s78, v38
	s_nop 1
	v_cndmask_b32_e64 v40, 0, 32, vcc
	v_ldexp_f32 v38, v38, v40
	v_log_f32_e32 v38, v38
	s_nop 0
	v_mul_f32_e32 v40, 0x3f317217, v38
	v_fma_f32 v40, v38, s87, -v40
	v_fmac_f32_e32 v40, 0x3377d1cf, v38
	v_fmac_f32_e32 v40, 0x3f317217, v38
	v_cmp_lt_f32_e64 s[10:11], |v38|, s97
	s_nop 1
	v_cndmask_b32_e64 v38, v38, v40, s[10:11]
	v_cndmask_b32_e32 v40, 0, v222, vcc
	v_sub_f32_e32 v38, v38, v40
	v_sub_f32_e32 v38, v39, v38
	v_mul_f32_e32 v39, 0x3d800000, v38
	v_mov_b32_e32 v40, v35
	s_nop 0
	v_mov_b32_dpp v39, v39 row_shr:1 row_mask:0xf bank_mask:0xf bound_ctrl:1
	v_fmac_f32_e32 v39, 0x3d800000, v38
	s_nop 1
	v_add_f32_dpp v39, v39, v39 row_shr:2 row_mask:0xf bank_mask:0xf bound_ctrl:1
	s_nop 1
	v_add_f32_dpp v39, v39, v39 row_shr:4 row_mask:0xf bank_mask:0xf bound_ctrl:1
	s_nop 1
	v_add_f32_dpp v39, v39, v39 row_shr:8 row_mask:0xf bank_mask:0xf bound_ctrl:1
	s_nop 1
	v_mov_b32_dpp v40, v39 row_bcast:15 row_mask:0xa bank_mask:0xf
	v_add_f32_e32 v39, v39, v40
	v_mov_b32_e32 v40, v35
	s_nop 0
	v_mov_b32_dpp v40, v39 row_bcast:31 row_mask:0xc bank_mask:0xf
	v_add_f32_e32 v39, v39, v40
	s_nop 0
	v_readlane_b32 s56, v39, 63
	s_nop 1
	v_sub_f32_e32 v40, s56, v39
	v_fmac_f32_e32 v40, 0x3d800000, v38
	v_cndmask_b32_e64 v89, v40, v39, s[0:1]
	global_store_dword v250, v89, s[100:101] offset:2560
	v_mov_b32_e32 v38, v167
	v_min_f32_e32 v39, 0, v38
	v_mul_f32_e64 v38, |v38|, s72
	v_exp_f32_e32 v38, v38
	s_nop 0
	v_add_f32_e32 v38, 1.0, v38
	v_cmp_gt_f32_e32 vcc, s78, v38
	s_nop 1
	v_cndmask_b32_e64 v40, 0, 32, vcc
	v_ldexp_f32 v38, v38, v40
; template <bool PHC>
; __device__ __forceinline__ void gla_pair(const KPD& kp, int l, int pair, unsigned char* lds, int tid, int lane, int wave, v4u& pz0, v4u& pz1, v4u& pw0, v4u& pw1, int next_pair) {
;     ...
;     for (int c = 0; c < 24; ++c) {
;         float pre = __int_as_float(__builtin_amdgcn_readlane(bvv, c));
; #pragma unroll
;         for (int r = 0; r < 16; ++r) pre += z[r] * __int_as_float(__builtin_amdgcn_readlane(wvv[(24 * r + c) >> 6], (24 * r + c) & 63));
;         const float la = (fminf(pre, 0.f) - __logf(1.f + __expf(-fabsf(pre)))) * (1.f / 16.f);
;         const float inc = wave_incl_scan(la);
;         const float total = __int_as_float(__builtin_amdgcn_readlane(__float_as_int(inc), 63));
;         bc[c] = dir ? (total - inc + la) : inc; tot[c] = total;
	v_log_f32_e32 v38, v38
	s_nop 0
	v_mul_f32_e32 v40, 0x3f317217, v38
	v_fma_f32 v40, v38, s87, -v40
	v_fmac_f32_e32 v40, 0x3377d1cf, v38
	v_fmac_f32_e32 v40, 0x3f317217, v38
	v_cmp_lt_f32_e64 s[10:11], |v38|, s97
	s_nop 1
	v_cndmask_b32_e64 v38, v38, v40, s[10:11]
	v_cndmask_b32_e32 v40, 0, v222, vcc
	v_sub_f32_e32 v38, v38, v40
	v_sub_f32_e32 v38, v39, v38
	v_mul_f32_e32 v39, 0x3d800000, v38
	v_mov_b32_e32 v40, v35
	s_nop 0
	v_mov_b32_dpp v39, v39 row_shr:1 row_mask:0xf bank_mask:0xf bound_ctrl:1
	v_fmac_f32_e32 v39, 0x3d800000, v38
	s_nop 1
	v_add_f32_dpp v39, v39, v39 row_shr:2 row_mask:0xf bank_mask:0xf bound_ctrl:1
	s_nop 1
	v_add_f32_dpp v39, v39, v39 row_shr:4 row_mask:0xf bank_mask:0xf bound_ctrl:1
	s_nop 1
	v_add_f32_dpp v39, v39, v39 row_shr:8 row_mask:0xf bank_mask:0xf bound_ctrl:1
	s_nop 1
	v_mov_b32_dpp v40, v39 row_bcast:15 row_mask:0xa bank_mask:0xf
	v_add_f32_e32 v39, v39, v40
	v_mov_b32_e32 v40, v35
	s_nop 0
	v_mov_b32_dpp v40, v39 row_bcast:31 row_mask:0xc bank_mask:0xf
	v_add_f32_e32 v39, v39, v40
	s_nop 0
	v_readlane_b32 s57, v39, 63
	s_nop 1
	v_sub_f32_e32 v40, s57, v39
	v_fmac_f32_e32 v40, 0x3d800000, v38
	v_cndmask_b32_e64 v91, v40, v39, s[0:1]
	global_store_dword v250, v91, s[100:101] offset:2816
	v_mov_b32_e32 v38, v230
	v_min_f32_e32 v39, 0, v38
	v_mul_f32_e64 v38, |v38|, s72
	v_exp_f32_e32 v38, v38
	s_nop 0
	v_add_f32_e32 v38, 1.0, v38
	v_cmp_gt_f32_e32 vcc, s78, v38
	s_nop 1
	v_cndmask_b32_e64 v40, 0, 32, vcc
	v_ldexp_f32 v38, v38, v40
	v_log_f32_e32 v38, v38
	s_nop 0
	v_mul_f32_e32 v40, 0x3f317217, v38
	v_fma_f32 v40, v38, s87, -v40
	v_fmac_f32_e32 v40, 0x3377d1cf, v38
	v_fmac_f32_e32 v40, 0x3f317217, v38
	v_cmp_lt_f32_e64 s[10:11], |v38|, s97
	s_nop 1
	v_cndmask_b32_e64 v38, v38, v40, s[10:11]
	v_cndmask_b32_e32 v40, 0, v222, vcc
	v_sub_f32_e32 v38, v38, v40
	v_sub_f32_e32 v38, v39, v38
	v_mul_f32_e32 v39, 0x3d800000, v38
	v_mov_b32_e32 v40, v35
	s_nop 0
	v_mov_b32_dpp v39, v39 row_shr:1 row_mask:0xf bank_mask:0xf bound_ctrl:1
	v_fmac_f32_e32 v39, 0x3d800000, v38
	s_nop 1
	v_add_f32_dpp v39, v39, v39 row_shr:2 row_mask:0xf bank_mask:0xf bound_ctrl:1
	s_nop 1
	v_add_f32_dpp v39, v39, v39 row_shr:4 row_mask:0xf bank_mask:0xf bound_ctrl:1
	s_nop 1
	v_add_f32_dpp v39, v39, v39 row_shr:8 row_mask:0xf bank_mask:0xf bound_ctrl:1
	s_nop 1
	v_mov_b32_dpp v40, v39 row_bcast:15 row_mask:0xa bank_mask:0xf
	v_add_f32_e32 v39, v39, v40
	v_mov_b32_e32 v40, v35
	s_nop 0
	v_mov_b32_dpp v40, v39 row_bcast:31 row_mask:0xc bank_mask:0xf
	v_add_f32_e32 v39, v39, v40
	s_nop 0
	v_readlane_b32 s59, v39, 63
	s_nop 1
	v_sub_f32_e32 v40, s59, v39
	v_fmac_f32_e32 v40, 0x3d800000, v38
	v_cndmask_b32_e64 v93, v40, v39, s[0:1]
	global_store_dword v250, v93, s[100:101] offset:3072
	v_mov_b32_e32 v38, v231
	v_min_f32_e32 v39, 0, v38
	v_mul_f32_e64 v38, |v38|, s72
	v_exp_f32_e32 v38, v38
	s_nop 0
	v_add_f32_e32 v38, 1.0, v38
	v_cmp_gt_f32_e32 vcc, s78, v38
	s_nop 1
	v_cndmask_b32_e64 v40, 0, 32, vcc
	v_ldexp_f32 v38, v38, v40
	v_log_f32_e32 v38, v38
	s_nop 0
	v_mul_f32_e32 v40, 0x3f317217, v38
	v_fma_f32 v40, v38, s87, -v40
	v_fmac_f32_e32 v40, 0x3377d1cf, v38
	v_fmac_f32_e32 v40, 0x3f317217, v38
	v_cmp_lt_f32_e64 s[10:11], |v38|, s97
	s_nop 1
	v_cndmask_b32_e64 v38, v38, v40, s[10:11]
	v_cndmask_b32_e32 v40, 0, v222, vcc
	v_sub_f32_e32 v38, v38, v40
	v_sub_f32_e32 v38, v39, v38
	v_mul_f32_e32 v39, 0x3d800000, v38
	v_mov_b32_e32 v40, v35
	s_nop 0
	v_mov_b32_dpp v39, v39 row_shr:1 row_mask:0xf bank_mask:0xf bound_ctrl:1
	v_fmac_f32_e32 v39, 0x3d800000, v38
	s_nop 1
	v_add_f32_dpp v39, v39, v39 row_shr:2 row_mask:0xf bank_mask:0xf bound_ctrl:1
	s_nop 1
	v_add_f32_dpp v39, v39, v39 row_shr:4 row_mask:0xf bank_mask:0xf bound_ctrl:1
	s_nop 1
	v_add_f32_dpp v39, v39, v39 row_shr:8 row_mask:0xf bank_mask:0xf bound_ctrl:1
	s_nop 1
	v_mov_b32_dpp v40, v39 row_bcast:15 row_mask:0xa bank_mask:0xf
	v_add_f32_e32 v39, v39, v40
	v_mov_b32_e32 v40, v35
	s_nop 0
	v_mov_b32_dpp v40, v39 row_bcast:31 row_mask:0xc bank_mask:0xf
	v_add_f32_e32 v39, v39, v40
	s_nop 0
	v_readlane_b32 s60, v39, 63
	s_nop 1
	v_sub_f32_e32 v40, s60, v39
	v_fmac_f32_e32 v40, 0x3d800000, v38
	v_cndmask_b32_e64 v94, v40, v39, s[0:1]
	global_store_dword v250, v94, s[100:101] offset:3328
	v_mov_b32_e32 v38, v232
	v_min_f32_e32 v39, 0, v38
	v_mul_f32_e64 v38, |v38|, s72
	v_exp_f32_e32 v38, v38
	s_nop 0
	v_add_f32_e32 v38, 1.0, v38
	v_cmp_gt_f32_e32 vcc, s78, v38
	s_nop 1
	v_cndmask_b32_e64 v40, 0, 32, vcc
	v_ldexp_f32 v38, v38, v40
	v_log_f32_e32 v38, v38
	s_nop 0
	v_mul_f32_e32 v40, 0x3f317217, v38
	v_fma_f32 v40, v38, s87, -v40
	v_fmac_f32_e32 v40, 0x3377d1cf, v38
	v_fmac_f32_e32 v40, 0x3f317217, v38
	v_cmp_lt_f32_e64 s[10:11], |v38|, s97
	s_nop 1
	v_cndmask_b32_e64 v38, v38, v40, s[10:11]
	v_cndmask_b32_e32 v40, 0, v222, vcc
	v_sub_f32_e32 v38, v38, v40
	v_sub_f32_e32 v38, v39, v38
	v_mul_f32_e32 v39, 0x3d800000, v38
	v_mov_b32_e32 v40, v35
	s_nop 0
	v_mov_b32_dpp v39, v39 row_shr:1 row_mask:0xf bank_mask:0xf bound_ctrl:1
	v_fmac_f32_e32 v39, 0x3d800000, v38
	s_nop 1
	v_add_f32_dpp v39, v39, v39 row_shr:2 row_mask:0xf bank_mask:0xf bound_ctrl:1
	s_nop 1
	v_add_f32_dpp v39, v39, v39 row_shr:4 row_mask:0xf bank_mask:0xf bound_ctrl:1
	s_nop 1
	v_add_f32_dpp v39, v39, v39 row_shr:8 row_mask:0xf bank_mask:0xf bound_ctrl:1
	s_nop 1
	v_mov_b32_dpp v40, v39 row_bcast:15 row_mask:0xa bank_mask:0xf
	v_add_f32_e32 v39, v39, v40
	v_mov_b32_e32 v40, v35
	s_nop 0
	v_mov_b32_dpp v40, v39 row_bcast:31 row_mask:0xc bank_mask:0xf
	v_add_f32_e32 v39, v39, v40
	s_nop 0
	v_readlane_b32 s61, v39, 63
	s_nop 1
	v_sub_f32_e32 v40, s61, v39
	v_fmac_f32_e32 v40, 0x3d800000, v38
	v_cndmask_b32_e64 v95, v40, v39, s[0:1]
; template <bool PHC>
; __device__ __forceinline__ void gla_pair(const KPD& kp, int l, int pair, unsigned char* lds, int tid, int lane, int wave, v4u& pz0, v4u& pz1, v4u& pw0, v4u& pw1, int next_pair) {
;     ...
;     for (int c = 0; c < 24; ++c) {
;         float pre = __int_as_float(__builtin_amdgcn_readlane(bvv, c));
; #pragma unroll
;         for (int r = 0; r < 16; ++r) pre += z[r] * __int_as_float(__builtin_amdgcn_readlane(wvv[(24 * r + c) >> 6], (24 * r + c) & 63));
;         const float la = (fminf(pre, 0.f) - __logf(1.f + __expf(-fabsf(pre)))) * (1.f / 16.f);
;         const float inc = wave_incl_scan(la);
;         const float total = __int_as_float(__builtin_amdgcn_readlane(__float_as_int(inc), 63));
;         bc[c] = dir ? (total - inc + la) : inc; tot[c] = total;
	global_store_dword v250, v95, s[100:101] offset:3584
	v_mov_b32_e32 v38, v233
	v_min_f32_e32 v39, 0, v38
	v_mul_f32_e64 v38, |v38|, s72
	v_exp_f32_e32 v38, v38
	s_nop 0
	v_add_f32_e32 v38, 1.0, v38
	v_cmp_gt_f32_e32 vcc, s78, v38
	s_nop 1
	v_cndmask_b32_e64 v40, 0, 32, vcc
	v_ldexp_f32 v38, v38, v40
	v_log_f32_e32 v38, v38
	s_nop 0
	v_mul_f32_e32 v40, 0x3f317217, v38
	v_fma_f32 v40, v38, s87, -v40
	v_fmac_f32_e32 v40, 0x3377d1cf, v38
	v_fmac_f32_e32 v40, 0x3f317217, v38
	v_cmp_lt_f32_e64 s[10:11], |v38|, s97
	s_nop 1
	v_cndmask_b32_e64 v38, v38, v40, s[10:11]
	v_cndmask_b32_e32 v40, 0, v222, vcc
	v_sub_f32_e32 v38, v38, v40
	v_sub_f32_e32 v38, v39, v38
	v_mul_f32_e32 v39, 0x3d800000, v38
	v_mov_b32_e32 v40, v35
	s_nop 0
	v_mov_b32_dpp v39, v39 row_shr:1 row_mask:0xf bank_mask:0xf bound_ctrl:1
	v_fmac_f32_e32 v39, 0x3d800000, v38
	s_nop 1
	v_add_f32_dpp v39, v39, v39 row_shr:2 row_mask:0xf bank_mask:0xf bound_ctrl:1
	s_nop 1
	v_add_f32_dpp v39, v39, v39 row_shr:4 row_mask:0xf bank_mask:0xf bound_ctrl:1
	s_nop 1
	v_add_f32_dpp v39, v39, v39 row_shr:8 row_mask:0xf bank_mask:0xf bound_ctrl:1
	s_nop 1
	v_mov_b32_dpp v40, v39 row_bcast:15 row_mask:0xa bank_mask:0xf
	v_add_f32_e32 v39, v39, v40
	v_mov_b32_e32 v40, v35
	s_nop 0
	v_mov_b32_dpp v40, v39 row_bcast:31 row_mask:0xc bank_mask:0xf
	v_add_f32_e32 v39, v39, v40
	s_nop 0
	v_readlane_b32 s62, v39, 63
	s_nop 1
	v_sub_f32_e32 v40, s62, v39
	v_fmac_f32_e32 v40, 0x3d800000, v38
	v_cndmask_b32_e64 v96, v40, v39, s[0:1]
	global_store_dword v250, v96, s[100:101] offset:3840
	v_mov_b32_e32 v38, v168
	v_min_f32_e32 v39, 0, v38
	v_mul_f32_e64 v38, |v38|, s72
	v_exp_f32_e32 v38, v38
	s_nop 0
	v_add_f32_e32 v38, 1.0, v38
	v_cmp_gt_f32_e32 vcc, s78, v38
	s_nop 1
	v_cndmask_b32_e64 v40, 0, 32, vcc
	v_ldexp_f32 v38, v38, v40
	v_log_f32_e32 v38, v38
	s_nop 0
	v_mul_f32_e32 v40, 0x3f317217, v38
	v_fma_f32 v40, v38, s87, -v40
	v_fmac_f32_e32 v40, 0x3377d1cf, v38
	v_fmac_f32_e32 v40, 0x3f317217, v38
	v_cmp_lt_f32_e64 s[10:11], |v38|, s97
	s_nop 1
	v_cndmask_b32_e64 v38, v38, v40, s[10:11]
	v_cndmask_b32_e32 v40, 0, v222, vcc
	v_sub_f32_e32 v38, v38, v40
	v_sub_f32_e32 v38, v39, v38
	v_mul_f32_e32 v39, 0x3d800000, v38
	v_mov_b32_e32 v40, v35
	s_nop 0
	v_mov_b32_dpp v39, v39 row_shr:1 row_mask:0xf bank_mask:0xf bound_ctrl:1
	v_fmac_f32_e32 v39, 0x3d800000, v38
	s_nop 1
	v_add_f32_dpp v39, v39, v39 row_shr:2 row_mask:0xf bank_mask:0xf bound_ctrl:1
	s_nop 1
	v_add_f32_dpp v39, v39, v39 row_shr:4 row_mask:0xf bank_mask:0xf bound_ctrl:1
	s_nop 1
	v_add_f32_dpp v39, v39, v39 row_shr:8 row_mask:0xf bank_mask:0xf bound_ctrl:1
	s_nop 1
	v_mov_b32_dpp v40, v39 row_bcast:15 row_mask:0xa bank_mask:0xf
	v_add_f32_e32 v39, v39, v40
	v_mov_b32_e32 v40, v35
	s_nop 0
	v_mov_b32_dpp v40, v39 row_bcast:31 row_mask:0xc bank_mask:0xf
	v_add_f32_e32 v39, v39, v40
	s_nop 0
	v_readlane_b32 s63, v39, 63
	s_nop 1
	v_sub_f32_e32 v40, s63, v39
	v_fmac_f32_e32 v40, 0x3d800000, v38
	v_cndmask_b32_e64 v97, v40, v39, s[0:1]
	global_store_dword v251, v97, s[100:101]
	v_mov_b32_e32 v38, v169
	v_min_f32_e32 v39, 0, v38
	v_mul_f32_e64 v38, |v38|, s72
	v_exp_f32_e32 v38, v38
	s_nop 0
	v_add_f32_e32 v38, 1.0, v38
	v_cmp_gt_f32_e32 vcc, s78, v38
	s_nop 1
	v_cndmask_b32_e64 v40, 0, 32, vcc
	v_ldexp_f32 v38, v38, v40
	v_log_f32_e32 v38, v38
	s_nop 0
	v_mul_f32_e32 v40, 0x3f317217, v38
	v_fma_f32 v40, v38, s87, -v40
	v_fmac_f32_e32 v40, 0x3377d1cf, v38
	v_fmac_f32_e32 v40, 0x3f317217, v38
	v_cmp_lt_f32_e64 s[10:11], |v38|, s97
	s_nop 1
	v_cndmask_b32_e64 v38, v38, v40, s[10:11]
	v_cndmask_b32_e32 v40, 0, v222, vcc
	v_sub_f32_e32 v38, v38, v40
	v_sub_f32_e32 v38, v39, v38
	v_mul_f32_e32 v39, 0x3d800000, v38
	v_mov_b32_e32 v40, v35
	s_nop 0
	v_mov_b32_dpp v39, v39 row_shr:1 row_mask:0xf bank_mask:0xf bound_ctrl:1
	v_fmac_f32_e32 v39, 0x3d800000, v38
	s_nop 1
	v_add_f32_dpp v39, v39, v39 row_shr:2 row_mask:0xf bank_mask:0xf bound_ctrl:1
	s_nop 1
	v_add_f32_dpp v39, v39, v39 row_shr:4 row_mask:0xf bank_mask:0xf bound_ctrl:1
	s_nop 1
	v_add_f32_dpp v39, v39, v39 row_shr:8 row_mask:0xf bank_mask:0xf bound_ctrl:1
	s_nop 1
	v_mov_b32_dpp v40, v39 row_bcast:15 row_mask:0xa bank_mask:0xf
	v_add_f32_e32 v39, v39, v40
	v_mov_b32_e32 v40, v35
	s_nop 0
	v_mov_b32_dpp v40, v39 row_bcast:31 row_mask:0xc bank_mask:0xf
	v_add_f32_e32 v39, v39, v40
	s_nop 0
	v_readlane_b32 s64, v39, 63
	s_nop 1
	v_sub_f32_e32 v40, s64, v39
	v_fmac_f32_e32 v40, 0x3d800000, v38
	v_cndmask_b32_e64 v98, v40, v39, s[0:1]
	global_store_dword v251, v98, s[100:101] offset:256
	v_mov_b32_e32 v38, v170
	v_min_f32_e32 v39, 0, v38
	v_mul_f32_e64 v38, |v38|, s72
	v_exp_f32_e32 v38, v38
	s_nop 0
	v_add_f32_e32 v38, 1.0, v38
	v_cmp_gt_f32_e32 vcc, s78, v38
	s_nop 1
	v_cndmask_b32_e64 v40, 0, 32, vcc
	v_ldexp_f32 v38, v38, v40
	v_log_f32_e32 v38, v38
	s_nop 0
	v_mul_f32_e32 v40, 0x3f317217, v38
	v_fma_f32 v40, v38, s87, -v40
	v_fmac_f32_e32 v40, 0x3377d1cf, v38
	v_fmac_f32_e32 v40, 0x3f317217, v38
	v_cmp_lt_f32_e64 s[10:11], |v38|, s97
	s_nop 1
	v_cndmask_b32_e64 v38, v38, v40, s[10:11]
	v_cndmask_b32_e32 v40, 0, v222, vcc
	v_sub_f32_e32 v38, v38, v40
	v_sub_f32_e32 v38, v39, v38
	v_mul_f32_e32 v39, 0x3d800000, v38
	v_mov_b32_e32 v40, v35
	s_nop 0
	v_mov_b32_dpp v39, v39 row_shr:1 row_mask:0xf bank_mask:0xf bound_ctrl:1
	v_fmac_f32_e32 v39, 0x3d800000, v38
	s_nop 1
	v_add_f32_dpp v39, v39, v39 row_shr:2 row_mask:0xf bank_mask:0xf bound_ctrl:1
	s_nop 1
	v_add_f32_dpp v39, v39, v39 row_shr:4 row_mask:0xf bank_mask:0xf bound_ctrl:1
	s_nop 1
	v_add_f32_dpp v39, v39, v39 row_shr:8 row_mask:0xf bank_mask:0xf bound_ctrl:1
	s_nop 1
	v_mov_b32_dpp v40, v39 row_bcast:15 row_mask:0xa bank_mask:0xf
; template <bool PHC>
; __device__ __forceinline__ void gla_pair(const KPD& kp, int l, int pair, unsigned char* lds, int tid, int lane, int wave, v4u& pz0, v4u& pz1, v4u& pw0, v4u& pw1, int next_pair) {
;     ...
;     for (int c = 0; c < 24; ++c) {
;         float pre = __int_as_float(__builtin_amdgcn_readlane(bvv, c));
; #pragma unroll
;         for (int r = 0; r < 16; ++r) pre += z[r] * __int_as_float(__builtin_amdgcn_readlane(wvv[(24 * r + c) >> 6], (24 * r + c) & 63));
;         const float la = (fminf(pre, 0.f) - __logf(1.f + __expf(-fabsf(pre)))) * (1.f / 16.f);
;         const float inc = wave_incl_scan(la);
;         const float total = __int_as_float(__builtin_amdgcn_readlane(__float_as_int(inc), 63));
;         bc[c] = dir ? (total - inc + la) : inc; tot[c] = total;
	v_add_f32_e32 v39, v39, v40
	v_mov_b32_e32 v40, v35
	s_nop 0
	v_mov_b32_dpp v40, v39 row_bcast:31 row_mask:0xc bank_mask:0xf
	v_add_f32_e32 v39, v39, v40
	s_nop 0
	v_readlane_b32 s65, v39, 63
	s_nop 1
	v_sub_f32_e32 v40, s65, v39
	v_fmac_f32_e32 v40, 0x3d800000, v38
	v_cndmask_b32_e64 v99, v40, v39, s[0:1]
	global_store_dword v251, v99, s[100:101] offset:512
	v_mov_b32_e32 v38, v171
	v_min_f32_e32 v39, 0, v38
	v_mul_f32_e64 v38, |v38|, s72
	v_exp_f32_e32 v38, v38
	s_nop 0
	v_add_f32_e32 v38, 1.0, v38
	v_cmp_gt_f32_e32 vcc, s78, v38
	s_nop 1
	v_cndmask_b32_e64 v40, 0, 32, vcc
	v_ldexp_f32 v38, v38, v40
	v_log_f32_e32 v38, v38
	s_nop 0
	v_mul_f32_e32 v40, 0x3f317217, v38
	v_fma_f32 v40, v38, s87, -v40
	v_fmac_f32_e32 v40, 0x3377d1cf, v38
	v_fmac_f32_e32 v40, 0x3f317217, v38
	v_cmp_lt_f32_e64 s[10:11], |v38|, s97
	s_nop 1
	v_cndmask_b32_e64 v38, v38, v40, s[10:11]
	v_cndmask_b32_e32 v40, 0, v222, vcc
	v_sub_f32_e32 v38, v38, v40
	v_sub_f32_e32 v38, v39, v38
	v_mul_f32_e32 v39, 0x3d800000, v38
	v_mov_b32_e32 v40, v35
	s_nop 0
	v_mov_b32_dpp v39, v39 row_shr:1 row_mask:0xf bank_mask:0xf bound_ctrl:1
	v_fmac_f32_e32 v39, 0x3d800000, v38
	s_nop 1
	v_add_f32_dpp v39, v39, v39 row_shr:2 row_mask:0xf bank_mask:0xf bound_ctrl:1
	s_nop 1
	v_add_f32_dpp v39, v39, v39 row_shr:4 row_mask:0xf bank_mask:0xf bound_ctrl:1
	s_nop 1
	v_add_f32_dpp v39, v39, v39 row_shr:8 row_mask:0xf bank_mask:0xf bound_ctrl:1
	s_nop 1
	v_mov_b32_dpp v40, v39 row_bcast:15 row_mask:0xa bank_mask:0xf
	v_add_f32_e32 v39, v39, v40
	v_mov_b32_e32 v40, v35
	s_nop 0
	v_mov_b32_dpp v40, v39 row_bcast:31 row_mask:0xc bank_mask:0xf
	v_add_f32_e32 v39, v39, v40
	s_nop 0
	v_readlane_b32 s66, v39, 63
	s_nop 1
	v_sub_f32_e32 v40, s66, v39
	v_fmac_f32_e32 v40, 0x3d800000, v38
	v_cndmask_b32_e64 v100, v40, v39, s[0:1]
	global_store_dword v251, v100, s[100:101] offset:768
	v_mov_b32_e32 v38, v234
	v_min_f32_e32 v39, 0, v38
	v_mul_f32_e64 v38, |v38|, s72
	v_exp_f32_e32 v38, v38
	s_nop 0
	v_add_f32_e32 v38, 1.0, v38
	v_cmp_gt_f32_e32 vcc, s78, v38
	s_nop 1
	v_cndmask_b32_e64 v40, 0, 32, vcc
	v_ldexp_f32 v38, v38, v40
	v_log_f32_e32 v38, v38
	s_nop 0
	v_mul_f32_e32 v40, 0x3f317217, v38
	v_fma_f32 v40, v38, s87, -v40
	v_fmac_f32_e32 v40, 0x3377d1cf, v38
	v_fmac_f32_e32 v40, 0x3f317217, v38
	v_cmp_lt_f32_e64 s[10:11], |v38|, s97
	s_nop 1
	v_cndmask_b32_e64 v38, v38, v40, s[10:11]
	v_cndmask_b32_e32 v40, 0, v222, vcc
	v_sub_f32_e32 v38, v38, v40
	v_sub_f32_e32 v38, v39, v38
	v_mul_f32_e32 v39, 0x3d800000, v38
	v_mov_b32_e32 v40, v35
	s_nop 0
	v_mov_b32_dpp v39, v39 row_shr:1 row_mask:0xf bank_mask:0xf bound_ctrl:1
	v_fmac_f32_e32 v39, 0x3d800000, v38
	s_nop 1
	v_add_f32_dpp v39, v39, v39 row_shr:2 row_mask:0xf bank_mask:0xf bound_ctrl:1
	s_nop 1
	v_add_f32_dpp v39, v39, v39 row_shr:4 row_mask:0xf bank_mask:0xf bound_ctrl:1
	s_nop 1
	v_add_f32_dpp v39, v39, v39 row_shr:8 row_mask:0xf bank_mask:0xf bound_ctrl:1
	s_nop 1
	v_mov_b32_dpp v40, v39 row_bcast:15 row_mask:0xa bank_mask:0xf
	v_add_f32_e32 v39, v39, v40
	v_mov_b32_e32 v40, v35
	s_nop 0
	v_mov_b32_dpp v40, v39 row_bcast:31 row_mask:0xc bank_mask:0xf
	v_add_f32_e32 v39, v39, v40
	s_nop 0
	v_readlane_b32 s67, v39, 63
	s_nop 1
	v_sub_f32_e32 v40, s67, v39
	v_fmac_f32_e32 v40, 0x3d800000, v38
	v_readlane_b32 s3, v31, 61
	v_cndmask_b32_e64 v101, v40, v39, s[0:1]
	global_store_dword v251, v101, s[100:101] offset:1024
	v_readlane_b32 s2, v31, 37
	s_nop 1
	v_pk_mul_f32 v[102:103], v[50:51], s[2:3]
	v_mov_b32_e32 v38, v235
	v_min_f32_e32 v39, 0, v38
	v_mul_f32_e64 v38, |v38|, s72
	v_exp_f32_e32 v38, v38
	s_nop 0
	v_add_f32_e32 v38, 1.0, v38
	v_cmp_gt_f32_e32 vcc, s78, v38
	s_nop 1
	v_cndmask_b32_e64 v40, 0, 32, vcc
	v_ldexp_f32 v38, v38, v40
	v_log_f32_e32 v38, v38
	s_nop 0
	v_mul_f32_e32 v40, 0x3f317217, v38
	v_fma_f32 v40, v38, s87, -v40
	v_fmac_f32_e32 v40, 0x3377d1cf, v38
	v_fmac_f32_e32 v40, 0x3f317217, v38
	v_cmp_lt_f32_e64 s[10:11], |v38|, s97
	s_nop 1
	v_cndmask_b32_e64 v38, v38, v40, s[10:11]
	v_cndmask_b32_e32 v40, 0, v222, vcc
	v_sub_f32_e32 v38, v38, v40
	v_sub_f32_e32 v38, v39, v38
	v_mul_f32_e32 v39, 0x3d800000, v38
	v_mov_b32_e32 v40, v35
	s_nop 0
	v_mov_b32_dpp v39, v39 row_shr:1 row_mask:0xf bank_mask:0xf bound_ctrl:1
	v_fmac_f32_e32 v39, 0x3d800000, v38
	s_nop 1
	v_add_f32_dpp v39, v39, v39 row_shr:2 row_mask:0xf bank_mask:0xf bound_ctrl:1
	s_nop 1
	v_add_f32_dpp v39, v39, v39 row_shr:4 row_mask:0xf bank_mask:0xf bound_ctrl:1
	s_nop 1
	v_add_f32_dpp v39, v39, v39 row_shr:8 row_mask:0xf bank_mask:0xf bound_ctrl:1
	s_nop 1
	v_mov_b32_dpp v40, v39 row_bcast:15 row_mask:0xa bank_mask:0xf
	v_add_f32_e32 v39, v39, v40
	v_mov_b32_e32 v40, v35
	s_nop 0
	v_mov_b32_dpp v40, v39 row_bcast:31 row_mask:0xc bank_mask:0xf
	v_add_f32_e32 v39, v39, v40
	s_nop 0
	v_readlane_b32 s68, v39, 63
	s_nop 1
	v_sub_f32_e32 v40, s68, v39
	v_fmac_f32_e32 v40, 0x3d800000, v38
	v_readlane_b32 s3, v31, 62
	v_cndmask_b32_e64 v102, v40, v39, s[0:1]
	global_store_dword v251, v102, s[100:101] offset:1280
	v_readlane_b32 s2, v31, 38
	s_nop 1
	v_pk_mul_f32 v[104:105], v[50:51], s[2:3]
	v_mov_b32_e32 v38, v236
	v_min_f32_e32 v39, 0, v38
	v_mul_f32_e64 v38, |v38|, s72
	v_exp_f32_e32 v38, v38
	s_nop 0
	v_add_f32_e32 v38, 1.0, v38
	v_cmp_gt_f32_e32 vcc, s78, v38
	s_nop 1
	v_cndmask_b32_e64 v40, 0, 32, vcc
	v_ldexp_f32 v38, v38, v40
	v_log_f32_e32 v38, v38
	s_nop 0
	v_mul_f32_e32 v40, 0x3f317217, v38
	v_fma_f32 v40, v38, s87, -v40
	v_fmac_f32_e32 v40, 0x3377d1cf, v38
	v_fmac_f32_e32 v40, 0x3f317217, v38
	v_cmp_lt_f32_e64 s[10:11], |v38|, s97
	s_nop 1
	v_cndmask_b32_e64 v38, v38, v40, s[10:11]
	v_cndmask_b32_e32 v40, 0, v222, vcc
	v_sub_f32_e32 v38, v38, v40
; __device__ __forceinline__ unsigned pk2(float lo, float hi) { return cvtpk(lo, hi); }
; __device__ __forceinline__ float lo16(unsigned w) { return __uint_as_float(w << 16); }
; __device__ __forceinline__ float hi16(unsigned w) { return __uint_as_float(w & 0xffff0000u); }
; template <bool PHC>
; __device__ __forceinline__ void gla_pair(const KPD& kp, int l, int pair, unsigned char* lds, int tid, int lane, int wave, v4u& pz0, v4u& pz1, v4u& pw0, v4u& pw1, int next_pair) {
;     ...
;     for (int c = 0; c < 24; ++c) {
;         float pre = __int_as_float(__builtin_amdgcn_readlane(bvv, c));
; #pragma unroll
;         for (int r = 0; r < 16; ++r) pre += z[r] * __int_as_float(__builtin_amdgcn_readlane(wvv[(24 * r + c) >> 6], (24 * r + c) & 63));
;         const float la = (fminf(pre, 0.f) - __logf(1.f + __expf(-fabsf(pre)))) * (1.f / 16.f);
;         const float inc = wave_incl_scan(la);
;         const float total = __int_as_float(__builtin_amdgcn_readlane(__float_as_int(inc), 63));
;         bc[c] = dir ? (total - inc + la) : inc; tot[c] = total;
;     }
;     float qv[24], kv[24];
; #pragma unroll
;     for (int i = 0; i < 3; ++i) {
;         qv[8 * i] = lo16(qraw[i].x); qv[8 * i + 1] = hi16(qraw[i].x); qv[8 * i + 2] = lo16(qraw[i].y); qv[8 * i + 3] = hi16(qraw[i].y);
;         qv[8 * i + 4] = lo16(qraw[i].z); qv[8 * i + 5] = hi16(qraw[i].z); qv[8 * i + 6] = lo16(qraw[i].w); qv[8 * i + 7] = hi16(qraw[i].w);
;         kv[8 * i] = lo16(kraw[i].x); kv[8 * i + 1] = hi16(kraw[i].x); kv[8 * i + 2] = lo16(kraw[i].y); kv[8 * i + 3] = hi16(kraw[i].y);
;         kv[8 * i + 4] = lo16(kraw[i].z); kv[8 * i + 5] = hi16(kraw[i].z); kv[8 * i + 6] = lo16(kraw[i].w); kv[8 * i + 7] = hi16(kraw[i].w); }
;     const size_t stbase = (size_t)((dir * 4 + b) * NCH + n);
;     if constexpr (!PHC) {
;         bf16* Vr = (bf16*)L;
;         bf16* KE = (bf16*)(L + 13312);
;         { unsigned kw[12];
; #pragma unroll
;           for (int i = 0; i < 12; ++i) kw[i] = pk2(kv[2 * i] * __expf(tot[2 * i] - bc[2 * i]), kv[2 * i + 1] * __expf(tot[2 * i + 1] - bc[2 * i + 1]));
;           v4u* ko = (v4u*)(KE + (dir * 64 + lane) * 56 + d0);
; #pragma unroll
;           for (int i = 0; i < 3; ++i) ko[i] = (v4u){kw[4 * i], kw[4 * i + 1], kw[4 * i + 2], kw[4 * i + 3]}; }
	v_sub_f32_e32 v38, v39, v38
	v_mul_f32_e32 v39, 0x3d800000, v38
	v_mov_b32_e32 v40, v35
	s_nop 0
	v_mov_b32_dpp v39, v39 row_shr:1 row_mask:0xf bank_mask:0xf bound_ctrl:1
	v_fmac_f32_e32 v39, 0x3d800000, v38
	s_nop 1
	v_add_f32_dpp v39, v39, v39 row_shr:2 row_mask:0xf bank_mask:0xf bound_ctrl:1
	s_nop 1
	v_add_f32_dpp v39, v39, v39 row_shr:4 row_mask:0xf bank_mask:0xf bound_ctrl:1
	s_nop 1
	v_add_f32_dpp v39, v39, v39 row_shr:8 row_mask:0xf bank_mask:0xf bound_ctrl:1
	s_nop 1
	v_mov_b32_dpp v40, v39 row_bcast:15 row_mask:0xa bank_mask:0xf
	v_add_f32_e32 v39, v39, v40
	v_mov_b32_e32 v40, v35
	s_nop 0
	v_mov_b32_dpp v40, v39 row_bcast:31 row_mask:0xc bank_mask:0xf
	v_add_f32_e32 v39, v39, v40
	s_nop 0
	v_readlane_b32 s69, v39, 63
	s_nop 1
	v_sub_f32_e32 v40, s69, v39
	v_fmac_f32_e32 v40, 0x3d800000, v38
	v_cndmask_b32_e64 v38, v40, v39, s[0:1]
	global_store_dword v251, v38, s[100:101] offset:1536
	v_sub_f32_e32 v38, s69, v38
	v_mul_f32_e32 v38, 0x3fb8aa3b, v38
	v_exp_f32_e32 v38, v38
	v_and_b32_e32 v62, 0xffff0000, v17
	v_lshlrev_b32_e32 v61, 16, v17
	v_sub_f32_e32 v17, s29, v79
	v_and_b32_e32 v60, 0xffff0000, v16
	v_mul_f32_e32 v17, 0x3fb8aa3b, v17
	v_lshlrev_b32_e32 v59, 16, v16
	v_sub_f32_e32 v16, s30, v68
	v_and_b32_e32 v58, 0xffff0000, v15
	v_mul_f32_e32 v16, 0x3fb8aa3b, v16
	v_lshlrev_b32_e32 v57, 16, v15
	v_sub_f32_e32 v15, s36, v66
	v_and_b32_e32 v56, 0xffff0000, v14
	v_mul_f32_e32 v15, 0x3fb8aa3b, v15
	v_lshlrev_b32_e32 v55, 16, v14
	v_sub_f32_e32 v14, s54, v65
	v_mul_f32_e32 v14, 0x3fb8aa3b, v14
	v_exp_f32_e32 v14, v14
	v_exp_f32_e32 v15, v15
	v_exp_f32_e32 v16, v16
	v_exp_f32_e32 v17, v17
	v_lshlrev_b32_e32 v52, 16, v43
	v_and_b32_e32 v43, 0xffff0000, v43
	v_lshlrev_b32_e32 v53, 16, v44
	v_and_b32_e32 v44, 0xffff0000, v44
	v_mov_b32_e32 v34, v237
	v_min_f32_e32 v39, 0, v34
	v_mul_f32_e64 v34, |v34|, s72
	v_exp_f32_e32 v34, v34
	v_lshlrev_b32_e32 v50, 16, v49
	v_and_b32_e32 v49, 0xffff0000, v49
	v_lshlrev_b32_e32 v51, 16, v42
	v_add_f32_e32 v34, 1.0, v34
	v_cmp_gt_f32_e32 vcc, s78, v34
	v_and_b32_e32 v42, 0xffff0000, v42
	v_lshlrev_b32_e32 v54, 16, v45
	v_cndmask_b32_e64 v40, 0, 32, vcc
	v_ldexp_f32 v34, v34, v40
	v_log_f32_e32 v34, v34
	v_and_b32_e32 v45, 0xffff0000, v45
	s_add_i32 s2, s52, s41
	s_mulk_i32 s2, 0x84
	v_mul_f32_e32 v40, 0x3f317217, v34
	v_fma_f32 v40, v34, s87, -v40
	v_fmac_f32_e32 v40, 0x3377d1cf, v34
	v_fmac_f32_e32 v40, 0x3f317217, v34
	v_cmp_lt_f32_e64 s[10:11], |v34|, s97
	s_add_i32 s2, s2, s53
	s_ashr_i32 s3, s2, 31
	v_cndmask_b32_e64 v34, v34, v40, s[10:11]
	v_cndmask_b32_e32 v40, 0, v222, vcc
	v_sub_f32_e32 v34, v34, v40
	v_sub_f32_e32 v34, v39, v34
	v_mul_f32_e32 v39, 0x3d800000, v34
	v_mov_b32_e32 v40, v35
	v_mul_f32_e32 v38, v38, v61
	v_mov_b32_dpp v39, v39 row_shr:1 row_mask:0xf bank_mask:0xf bound_ctrl:1
	v_fmac_f32_e32 v39, 0x3d800000, v34
	s_nop 1
	v_add_f32_dpp v39, v39, v39 row_shr:2 row_mask:0xf bank_mask:0xf bound_ctrl:1
	s_nop 1
	v_add_f32_dpp v39, v39, v39 row_shr:4 row_mask:0xf bank_mask:0xf bound_ctrl:1
	s_nop 1
	v_add_f32_dpp v39, v39, v39 row_shr:8 row_mask:0xf bank_mask:0xf bound_ctrl:1
	s_nop 1
	v_mov_b32_dpp v40, v39 row_bcast:15 row_mask:0xa bank_mask:0xf
	v_add_f32_e32 v39, v39, v40
	v_mov_b32_e32 v40, v35
	s_nop 0
	v_mov_b32_dpp v40, v39 row_bcast:31 row_mask:0xc bank_mask:0xf
	v_add_f32_e32 v39, v39, v40
	s_nop 0
	v_readlane_b32 s72, v39, 63
	s_nop 1
	v_sub_f32_e32 v40, s72, v39
	v_fmac_f32_e32 v40, 0x3d800000, v34
	v_cndmask_b32_e64 v34, v40, v39, s[0:1]
	global_store_dword v251, v34, s[100:101] offset:1792
	v_lshlrev_b32_e32 v39, 16, v46
	v_and_b32_e32 v40, 0xffff0000, v46
	v_mul_f32_e32 v14, v14, v39
	v_mul_f32_e32 v15, v15, v40
	v_cvt_pk_bf16_f32 v14, v14, v15
	v_sub_f32_e32 v15, s34, v67
	v_mul_f32_e32 v15, 0x3fb8aa3b, v15
	v_exp_f32_e32 v15, v15
	v_and_b32_e32 v46, 0xffff0000, v47
	v_mul_f32_e32 v16, v16, v46
	v_lshlrev_b32_e32 v47, 16, v48
	v_mul_f32_e32 v15, v15, v41
	v_cvt_pk_bf16_f32 v15, v15, v16
	v_sub_f32_e32 v16, s28, v69
	v_mul_f32_e32 v16, 0x3fb8aa3b, v16
	v_exp_f32_e32 v16, v16
	v_and_b32_e32 v48, 0xffff0000, v48
	v_mul_f32_e32 v17, v17, v48
	v_sub_f32_e32 v39, s35, v83
	v_mul_f32_e32 v16, v16, v47
	v_cvt_pk_bf16_f32 v16, v16, v17
	v_sub_f32_e32 v17, s31, v81
	v_mul_f32_e32 v17, 0x3fb8aa3b, v17
	v_mul_f32_e32 v39, 0x3fb8aa3b, v39
	v_exp_f32_e32 v17, v17
	v_exp_f32_e32 v39, v39
	v_sub_f32_e32 v40, s55, v87
	v_mul_f32_e32 v40, 0x3fb8aa3b, v40
	v_mul_f32_e32 v17, v17, v50
	v_mul_f32_e32 v39, v39, v49
	v_cvt_pk_bf16_f32 v17, v17, v39
	v_sub_f32_e32 v39, s37, v85
	v_mul_f32_e32 v39, 0x3fb8aa3b, v39
	v_exp_f32_e32 v39, v39
	v_exp_f32_e32 v40, v40
	v_sub_f32_e32 v34, s72, v34
	v_mul_f32_e32 v34, 0x3fb8aa3b, v34
	v_mul_f32_e32 v39, v39, v51
	v_mul_f32_e32 v40, v40, v42
	v_cvt_pk_bf16_f32 v42, v39, v40
	v_sub_f32_e32 v39, s56, v89
	v_sub_f32_e32 v40, s57, v91
	v_mul_f32_e32 v39, 0x3fb8aa3b, v39
	v_mul_f32_e32 v40, 0x3fb8aa3b, v40
	v_exp_f32_e32 v39, v39
	v_exp_f32_e32 v40, v40
	v_exp_f32_e32 v34, v34
	v_mul_f32_e32 v39, v39, v52
	v_mul_f32_e32 v40, v40, v43
	v_cvt_pk_bf16_f32 v43, v39, v40
	v_sub_f32_e32 v39, s59, v93
	v_sub_f32_e32 v40, s60, v94
	v_mul_f32_e32 v39, 0x3fb8aa3b, v39
	v_mul_f32_e32 v40, 0x3fb8aa3b, v40
	v_exp_f32_e32 v39, v39
	v_exp_f32_e32 v40, v40
	v_mul_f32_e32 v34, v34, v62
	v_cvt_pk_bf16_f32 v49, v38, v34
	v_mul_f32_e32 v39, v39, v53
	v_mul_f32_e32 v40, v40, v44
	v_cvt_pk_bf16_f32 v44, v39, v40
	v_sub_f32_e32 v39, s61, v95
	v_sub_f32_e32 v40, s62, v96
	v_mul_f32_e32 v39, 0x3fb8aa3b, v39
	v_mul_f32_e32 v40, 0x3fb8aa3b, v40
	v_exp_f32_e32 v39, v39
	v_exp_f32_e32 v40, v40
	v_mul_f32_e32 v39, v39, v54
	v_mul_f32_e32 v40, v40, v45
	v_cvt_pk_bf16_f32 v45, v39, v40
	v_sub_f32_e32 v39, s63, v97
	v_sub_f32_e32 v40, s64, v98
	v_mul_f32_e32 v39, 0x3fb8aa3b, v39
	v_mul_f32_e32 v40, 0x3fb8aa3b, v40
	v_exp_f32_e32 v39, v39
	v_exp_f32_e32 v40, v40
	v_mul_f32_e32 v39, v39, v55
	v_mul_f32_e32 v40, v40, v56
	v_cvt_pk_bf16_f32 v46, v39, v40
	v_sub_f32_e32 v39, s65, v99
	v_sub_f32_e32 v40, s66, v100
	v_mul_f32_e32 v39, 0x3fb8aa3b, v39
	v_mul_f32_e32 v40, 0x3fb8aa3b, v40
	v_exp_f32_e32 v39, v39
	v_exp_f32_e32 v40, v40
	v_mul_f32_e32 v39, v39, v57
	v_mul_f32_e32 v40, v40, v58
	v_cvt_pk_bf16_f32 v47, v39, v40
	v_sub_f32_e32 v39, s67, v101
	v_sub_f32_e32 v40, s68, v102
	v_mul_f32_e32 v39, 0x3fb8aa3b, v39
	v_mul_f32_e32 v40, 0x3fb8aa3b, v40
	v_exp_f32_e32 v39, v39
	v_exp_f32_e32 v40, v40
	v_mul_f32_e32 v39, v39, v59
	v_mul_f32_e32 v40, v40, v60
	v_cvt_pk_bf16_f32 v48, v39, v40
	ds_write_b128 v122, v[14:17] offset:13312
	ds_write_b128 v122, v[42:45] offset:13328
	ds_write_b128 v122, v[46:49] offset:13344
	s_and_saveexec_b64 s[10:11], s[4:5]
	s_cbranch_execz .LBB0_266
; template <bool PHC>
; __device__ __forceinline__ void gla_pair(const KPD& kp, int l, int pair, unsigned char* lds, int tid, int lane, int wave, v4u& pz0, v4u& pz1, v4u& pw0, v4u& pw1, int next_pair) {
;     ...
;         if (lane == 0) {
; #pragma unroll
;             for (int c = 0; c < 24; ++c) DEC[stbase * 192 + h * 48 + d0 + c] = __expf(tot[c]);
;         }
	s_mul_i32 s13, s2, 0x300
	s_mul_hi_i32 s12, s2, 0x300
	s_add_u32 s13, s50, s13
	s_addc_u32 s12, s49, s12
	s_lshl_b32 s49, s51, 2
	v_mul_f32_e32 v14, s54, v223
	v_mul_f32_e32 v15, s36, v223
	v_mul_f32_e32 v16, s34, v223
	v_mul_f32_e32 v17, s30, v223
	s_add_u32 s13, s13, s49
	v_exp_f32_e32 v14, v14
	v_exp_f32_e32 v15, v15
	v_exp_f32_e32 v16, v16
	v_exp_f32_e32 v17, v17
	s_addc_u32 s12, s12, 0
	s_lshl_b32 s49, s40, 2
	s_add_u32 s50, s13, s49
	s_addc_u32 s51, s12, 0
	v_mov_b32_e32 v34, 0x19b00000
	global_store_dwordx4 v34, v[14:17], s[50:51]
	s_add_u32 s12, s50, 0x19b00000
	s_addc_u32 s13, s51, 0
	v_mul_f32_e32 v14, s28, v223
	v_mul_f32_e32 v15, s29, v223
	v_mul_f32_e32 v16, s31, v223
	v_mul_f32_e32 v17, s35, v223
	v_exp_f32_e32 v14, v14
	v_exp_f32_e32 v15, v15
	v_exp_f32_e32 v16, v16
	v_exp_f32_e32 v17, v17
	global_store_dwordx4 v35, v[14:17], s[12:13] offset:16
	s_nop 1
	v_mul_f32_e32 v14, s37, v223
	v_mul_f32_e32 v15, s55, v223
	v_mul_f32_e32 v16, s56, v223
	v_mul_f32_e32 v17, s57, v223
	v_exp_f32_e32 v14, v14
	v_exp_f32_e32 v15, v15
	v_exp_f32_e32 v16, v16
	v_exp_f32_e32 v17, v17
	global_store_dwordx4 v35, v[14:17], s[12:13] offset:32
	s_nop 1
	v_mul_f32_e32 v14, s59, v223
	v_mul_f32_e32 v15, s60, v223
	v_mul_f32_e32 v16, s61, v223
	v_mul_f32_e32 v17, s62, v223
	v_exp_f32_e32 v14, v14
	v_exp_f32_e32 v15, v15
	v_exp_f32_e32 v16, v16
	v_exp_f32_e32 v17, v17
	global_store_dwordx4 v35, v[14:17], s[12:13] offset:48
	s_nop 1
	v_mul_f32_e32 v14, s63, v223
	v_mul_f32_e32 v15, s64, v223
	v_mul_f32_e32 v16, s65, v223
	v_mul_f32_e32 v17, s66, v223
	v_exp_f32_e32 v14, v14
	v_exp_f32_e32 v15, v15
	v_exp_f32_e32 v16, v16
	v_exp_f32_e32 v17, v17
	global_store_dwordx4 v35, v[14:17], s[12:13] offset:64
	s_nop 1
	v_mul_f32_e32 v14, s67, v223
	v_mul_f32_e32 v15, s68, v223
	v_mul_f32_e32 v16, s69, v223
	v_mul_f32_e32 v17, s72, v223
	v_exp_f32_e32 v14, v14
	v_exp_f32_e32 v15, v15
	v_exp_f32_e32 v16, v16
	v_exp_f32_e32 v17, v17
	global_store_dwordx4 v35, v[14:17], s[12:13] offset:80
